# t4 + w_in K-loop: LDS-DMA issue before ds_reads in each load segment
# baseline (speedup 1.0000x reference)
; #define PG8_STAGE(bufoff, gbase, voff) do { _Pragma("unroll") for (int _i = 0; _i < 2; ++_i) \
;         __builtin_amdgcn_global_load_lds((const unsigned*)((const char*)(gbase) + (voff)[_i]), (PG8_LAS unsigned*)(lds + (bufoff) + ldsw + _i * 8192), 16, 0, 0); } while (0)
; #define PG8_LDA(dst, b, h) do { _Pragma("unroll") for (int m = 0; m < 4; ++m) _Pragma("unroll") for (int k = 0; k < 2; ++k) dst[m][k] = *(const PG8_LAS bf16x8*)(lds + PG8_SA(b, h) + aoff + m * 2048 + k * 1024); } while (0)
; #define PG8_LDB(dst, b, h) do { _Pragma("unroll") for (int n = 0; n < 2; ++n) _Pragma("unroll") for (int k = 0; k < 2; ++k) dst[n][k] = *(const PG8_LAS bf16x8*)(lds + PG8_SB(b, h) + boff + n * 2048 + k * 1024); } while (0)
; #define PG8_MMA(ai, bj, At, Bt) do { __builtin_amdgcn_s_setprio(1); _Pragma("unroll") for (int m = 0; m < 4; ++m) _Pragma("unroll") for (int n = 0; n < 2; ++n) _Pragma("unroll") for (int k = 0; k < 2; ++k) \
;         acc[ai][bj][m][n] = __builtin_amdgcn_mfma_f32_16x16x32_bf16(Bt[n][k], At[m][k], acc[ai][bj][m][n], 0, 0, 0); __builtin_amdgcn_s_setprio(0); } while (0)
; #define PG8_WAIT_V(n) asm volatile("s_waitcnt vmcnt(" #n ")" ::: "memory")
; #define PG8_BAR __builtin_amdgcn_s_barrier()
; template <class Epi, class Sched, bool ALIGN_EPI = false, bool SP2 = false>
; __device__ __forceinline__ void gemm_phase(PG8_LAS unsigned char* lds, const Gemm g, const Sched& S, const Epi& E) {
;     ...
;         for (int t = 0; t < nt; t += 2) {
;             const bool last = (t == nt - 2);
;             const char* a1 = cA + (size_t)(t + 1) * kstep;
;             const char* a2 = last ? nA : cA + (size_t)(t + 2) * kstep; const char* b2 = last ? nB : cB + (size_t)(t + 2) * kstep;
;             const char* a3 = a2 + kstep; const char* b3 = b2 + kstep;
;             if (last && has_next) S.a_ready(nxt);
;             if constexpr (SP2) {
;             PG8_LDB(B0, 0, 0); PG8_LDB(B1, 0, 1); PG8_SCHED; PG8_LDA(At, 0, 0); PG8_STAGE(PG8_SA(1, 1), a1 + hstep, voffA);
;             PG8_WAIT_V(8); PG8_WAIT_L(0); PG8_BAR; PG8_MMA(0, 0, At, B0); PG8_MMA(0, 1, At, B1); PG8_BAR; PG8_SCHED;
;             PG8_LDA(At, 0, 1); PG8_STAGE(PG8_SB(0, 0), b2, voffB); PG8_STAGE(PG8_SB(0, 1), b2 + hstep, voffB); PG8_STAGE(PG8_SA(0, 0), a2, voffA);
;             PG8_WAIT_V(8); PG8_WAIT_L(0); PG8_BAR; PG8_MMA(1, 0, At, B0); PG8_MMA(1, 1, At, B1); PG8_BAR; PG8_SCHED;
.LBB0_398:
	s_lshl_b32 s54, s43, 7
	s_add_u32 s55, s30, s54
	s_addc_u32 s56, s31, 0
	s_add_u32 s57, s55, 0x100
	s_addc_u32 s58, s56, 0
	s_and_b64 s[52:53], s[12:13], exec
	s_cselect_b32 s53, s58, s1
	s_cselect_b32 s52, s57, s2
	s_add_u32 s54, s34, s54
	s_addc_u32 s57, s35, 0
	s_add_u32 s54, s54, 0x100
	s_addc_u32 s57, s57, 0
	s_and_b64 s[12:13], s[12:13], exec
	s_cselect_b32 s13, s57, s3
	s_cselect_b32 s12, s54, s41
	s_add_i32 s57, 0, 0x10000
	s_add_i32 s58, 0, 0x14000
	s_add_u32 s54, s55, 0x80080
	s_addc_u32 s55, s56, 0
	v_lshl_add_u64 v[224:225], s[54:55], 0, v[156:157]
	s_add_i32 m0, s29, 0xc000
	global_load_lds_dwordx4 v[224:225], off
	v_lshl_add_u64 v[224:225], s[54:55], 0, v[160:161]
	s_add_i32 m0, s29, 0xe000
	s_nop 0
	global_load_lds_dwordx4 v[224:225], off
	v_add_u32_e32 v0, s57, v181
	ds_read_b128 v[132:135], v0
	ds_read_b128 v[136:139], v0 offset:1024
	ds_read_b128 v[140:143], v0 offset:2048
	ds_read_b128 v[144:147], v0 offset:3072
	v_add_u32_e32 v0, s58, v181
	ds_read_b128 v[148:151], v0
	ds_read_b128 v[152:155], v0 offset:1024
	ds_read_b128 v[168:171], v0 offset:2048
	ds_read_b128 v[172:175], v0 offset:3072
	ds_read_b128 v[176:179], v187
	ds_read_b128 v[188:191], v187 offset:1024
	ds_read_b128 v[192:195], v187 offset:2048
	ds_read_b128 v[196:199], v187 offset:3072
	ds_read_b128 v[200:203], v187 offset:4096
	ds_read_b128 v[204:207], v187 offset:5120
	ds_read_b128 v[208:211], v187 offset:6144
	ds_read_b128 v[220:223], v187 offset:7168
	s_waitcnt vmcnt(8)
	s_waitcnt lgkmcnt(0)
	s_barrier
	s_setprio 1
	s_waitcnt lgkmcnt(0)
	v_mfma_f32_16x16x32_bf16 v[128:131], v[132:135], v[176:179], v[128:131]
	v_mfma_f32_16x16x32_bf16 v[124:127], v[140:143], v[176:179], v[124:127]
	v_mfma_f32_16x16x32_bf16 v[120:123], v[132:135], v[192:195], v[120:123]
	v_mfma_f32_16x16x32_bf16 v[116:119], v[140:143], v[192:195], v[116:119]
	v_mfma_f32_16x16x32_bf16 v[112:115], v[132:135], v[200:203], v[112:115]
	v_mfma_f32_16x16x32_bf16 v[108:111], v[140:143], v[200:203], v[108:111]
	v_mfma_f32_16x16x32_bf16 v[104:107], v[132:135], v[208:211], v[104:107]
	v_mfma_f32_16x16x32_bf16 v[100:103], v[140:143], v[208:211], v[100:103]
	v_mfma_f32_16x16x32_bf16 v[128:131], v[136:139], v[188:191], v[128:131]
	v_mfma_f32_16x16x32_bf16 v[124:127], v[144:147], v[188:191], v[124:127]
	v_mfma_f32_16x16x32_bf16 v[120:123], v[136:139], v[196:199], v[120:123]
	v_mfma_f32_16x16x32_bf16 v[116:119], v[144:147], v[196:199], v[116:119]
	v_mfma_f32_16x16x32_bf16 v[112:115], v[136:139], v[204:207], v[112:115]
	v_mfma_f32_16x16x32_bf16 v[108:111], v[144:147], v[204:207], v[108:111]
	v_mfma_f32_16x16x32_bf16 v[104:107], v[136:139], v[220:223], v[104:107]
	v_mfma_f32_16x16x32_bf16 v[100:103], v[144:147], v[220:223], v[100:103]
	s_setprio 0
	s_setprio 1
	v_mfma_f32_16x16x32_bf16 v[96:99], v[148:151], v[176:179], v[96:99]
	v_mfma_f32_16x16x32_bf16 v[92:95], v[168:171], v[176:179], v[92:95]
	v_mfma_f32_16x16x32_bf16 v[88:91], v[148:151], v[192:195], v[88:91]
	v_mfma_f32_16x16x32_bf16 v[84:87], v[168:171], v[192:195], v[84:87]
	v_mfma_f32_16x16x32_bf16 v[80:83], v[148:151], v[200:203], v[80:83]
	v_mfma_f32_16x16x32_bf16 v[76:79], v[168:171], v[200:203], v[76:79]
	v_mfma_f32_16x16x32_bf16 v[72:75], v[148:151], v[208:211], v[72:75]
	v_mfma_f32_16x16x32_bf16 v[68:71], v[168:171], v[208:211], v[68:71]
	v_mfma_f32_16x16x32_bf16 v[96:99], v[152:155], v[188:191], v[96:99]
	v_mfma_f32_16x16x32_bf16 v[92:95], v[172:175], v[188:191], v[92:95]
	v_mfma_f32_16x16x32_bf16 v[88:91], v[152:155], v[196:199], v[88:91]
	v_mfma_f32_16x16x32_bf16 v[84:87], v[172:175], v[196:199], v[84:87]
	v_mfma_f32_16x16x32_bf16 v[80:83], v[152:155], v[204:207], v[80:83]
	v_mfma_f32_16x16x32_bf16 v[76:79], v[172:175], v[204:207], v[76:79]
	v_mfma_f32_16x16x32_bf16 v[72:75], v[152:155], v[220:223], v[72:75]
	v_mfma_f32_16x16x32_bf16 v[68:71], v[172:175], v[220:223], v[68:71]
	s_setprio 0
	s_barrier
	s_add_i32 s54, s57, s15
	v_lshl_add_u64 v[224:225], s[12:13], 0, v[158:159]
	s_mov_b32 m0, s54
	global_load_lds_dwordx4 v[224:225], off
	s_add_i32 m0, s54, 0x2000
	s_add_u32 s54, s12, 0x80000
	v_lshl_add_u64 v[226:227], s[12:13], 0, v[162:163]
	s_addc_u32 s55, s13, 0
	s_add_i32 s56, s58, s15
	global_load_lds_dwordx4 v[226:227], off
	v_lshl_add_u64 v[228:229], s[54:55], 0, v[158:159]
	s_mov_b32 m0, s56
	v_lshl_add_u64 v[230:231], s[52:53], 0, v[160:161]
	global_load_lds_dwordx4 v[228:229], off
	v_lshl_add_u64 v[228:229], s[54:55], 0, v[162:163]
	s_add_i32 m0, s56, 0x2000
	s_nop 0
	global_load_lds_dwordx4 v[228:229], off
	v_lshl_add_u64 v[228:229], s[52:53], 0, v[156:157]
	s_mov_b32 m0, s29
	s_nop 0
	global_load_lds_dwordx4 v[228:229], off
	s_mov_b32 m0, s65
	s_nop 0
	global_load_lds_dwordx4 v[230:231], off
	ds_read_b128 v[176:179], v187 offset:16384
	ds_read_b128 v[188:191], v187 offset:17408
	ds_read_b128 v[192:195], v187 offset:18432
	ds_read_b128 v[196:199], v187 offset:19456
	ds_read_b128 v[200:203], v187 offset:20480
	ds_read_b128 v[204:207], v187 offset:21504
	ds_read_b128 v[208:211], v187 offset:22528
	ds_read_b128 v[220:223], v187 offset:23552
	s_waitcnt vmcnt(8)
	s_waitcnt lgkmcnt(0)
	s_barrier
; #define PG8_STAGE(bufoff, gbase, voff) do { _Pragma("unroll") for (int _i = 0; _i < 2; ++_i) \
;         __builtin_amdgcn_global_load_lds((const unsigned*)((const char*)(gbase) + (voff)[_i]), (PG8_LAS unsigned*)(lds + (bufoff) + ldsw + _i * 8192), 16, 0, 0); } while (0)
; #define PG8_LDA(dst, b, h) do { _Pragma("unroll") for (int m = 0; m < 4; ++m) _Pragma("unroll") for (int k = 0; k < 2; ++k) dst[m][k] = *(const PG8_LAS bf16x8*)(lds + PG8_SA(b, h) + aoff + m * 2048 + k * 1024); } while (0)
; #define PG8_LDB(dst, b, h) do { _Pragma("unroll") for (int n = 0; n < 2; ++n) _Pragma("unroll") for (int k = 0; k < 2; ++k) dst[n][k] = *(const PG8_LAS bf16x8*)(lds + PG8_SB(b, h) + boff + n * 2048 + k * 1024); } while (0)
; #define PG8_MMA(ai, bj, At, Bt) do { __builtin_amdgcn_s_setprio(1); _Pragma("unroll") for (int m = 0; m < 4; ++m) _Pragma("unroll") for (int n = 0; n < 2; ++n) _Pragma("unroll") for (int k = 0; k < 2; ++k) \
;         acc[ai][bj][m][n] = __builtin_amdgcn_mfma_f32_16x16x32_bf16(Bt[n][k], At[m][k], acc[ai][bj][m][n], 0, 0, 0); __builtin_amdgcn_s_setprio(0); } while (0)
; #define PG8_WAIT_V(n) asm volatile("s_waitcnt vmcnt(" #n ")" ::: "memory")
; #define PG8_WAIT_L(n) asm volatile("s_waitcnt lgkmcnt(" #n ")" ::: "memory")
; #define PG8_BAR __builtin_amdgcn_s_barrier()
; #define PG8_SCHED __builtin_amdgcn_sched_barrier(0)
; template <class Epi, class Sched, bool ALIGN_EPI = false, bool SP2 = false>
; __device__ __forceinline__ void gemm_phase(PG8_LAS unsigned char* lds, const Gemm g, const Sched& S, const Epi& E) {
;     ...
;             PG8_WAIT_V(8); PG8_WAIT_L(0); PG8_BAR; PG8_MMA(1, 0, At, B0); PG8_MMA(1, 1, At, B1); PG8_BAR; PG8_SCHED;
;             PG8_LDB(B0, 1, 0); PG8_LDB(B1, 1, 1); PG8_SCHED; PG8_LDA(At, 1, 0); PG8_STAGE(PG8_SA(0, 1), a2 + hstep, voffA);
;             PG8_WAIT_V(8); PG8_WAIT_L(0); PG8_BAR; PG8_MMA(0, 0, At, B0); PG8_MMA(0, 1, At, B1); PG8_BAR; PG8_SCHED;
	s_setprio 1
	s_waitcnt lgkmcnt(0)
	v_mfma_f32_16x16x32_bf16 v[62:65], v[132:135], v[176:179], v[62:65]
	v_mfma_f32_16x16x32_bf16 v[58:61], v[140:143], v[176:179], v[58:61]
	v_mfma_f32_16x16x32_bf16 v[54:57], v[132:135], v[192:195], v[54:57]
	v_mfma_f32_16x16x32_bf16 v[50:53], v[140:143], v[192:195], v[50:53]
	v_mfma_f32_16x16x32_bf16 v[46:49], v[132:135], v[200:203], v[46:49]
	v_mfma_f32_16x16x32_bf16 v[42:45], v[140:143], v[200:203], v[42:45]
	v_mfma_f32_16x16x32_bf16 v[38:41], v[132:135], v[208:211], v[38:41]
	v_mfma_f32_16x16x32_bf16 v[34:37], v[140:143], v[208:211], v[34:37]
	v_mfma_f32_16x16x32_bf16 v[62:65], v[136:139], v[188:191], v[62:65]
	v_mfma_f32_16x16x32_bf16 v[58:61], v[144:147], v[188:191], v[58:61]
	v_mfma_f32_16x16x32_bf16 v[54:57], v[136:139], v[196:199], v[54:57]
	v_mfma_f32_16x16x32_bf16 v[50:53], v[144:147], v[196:199], v[50:53]
	v_mfma_f32_16x16x32_bf16 v[46:49], v[136:139], v[204:207], v[46:49]
	v_mfma_f32_16x16x32_bf16 v[42:45], v[144:147], v[204:207], v[42:45]
	v_mfma_f32_16x16x32_bf16 v[38:41], v[136:139], v[220:223], v[38:41]
	v_mfma_f32_16x16x32_bf16 v[34:37], v[144:147], v[220:223], v[34:37]
	s_setprio 0
	s_setprio 1
	v_mfma_f32_16x16x32_bf16 v[30:33], v[148:151], v[176:179], v[30:33]
	v_mfma_f32_16x16x32_bf16 v[26:29], v[168:171], v[176:179], v[26:29]
	v_mfma_f32_16x16x32_bf16 v[22:25], v[148:151], v[192:195], v[22:25]
	v_mfma_f32_16x16x32_bf16 v[18:21], v[168:171], v[192:195], v[18:21]
	v_mfma_f32_16x16x32_bf16 v[14:17], v[148:151], v[200:203], v[14:17]
	v_mfma_f32_16x16x32_bf16 v[10:13], v[168:171], v[200:203], v[10:13]
	v_mfma_f32_16x16x32_bf16 v[6:9], v[148:151], v[208:211], v[6:9]
	v_mfma_f32_16x16x32_bf16 v[2:5], v[168:171], v[208:211], v[2:5]
	v_mfma_f32_16x16x32_bf16 v[30:33], v[152:155], v[188:191], v[30:33]
	v_mfma_f32_16x16x32_bf16 v[26:29], v[172:175], v[188:191], v[26:29]
	v_mfma_f32_16x16x32_bf16 v[22:25], v[152:155], v[196:199], v[22:25]
	v_mfma_f32_16x16x32_bf16 v[18:21], v[172:175], v[196:199], v[18:21]
	v_mfma_f32_16x16x32_bf16 v[14:17], v[152:155], v[204:207], v[14:17]
	v_mfma_f32_16x16x32_bf16 v[10:13], v[172:175], v[204:207], v[10:13]
	v_mfma_f32_16x16x32_bf16 v[6:9], v[152:155], v[220:223], v[6:9]
	v_mfma_f32_16x16x32_bf16 v[2:5], v[172:175], v[220:223], v[2:5]
	s_setprio 0
	s_barrier
	s_add_i32 s54, 0, 0x18000
	s_add_i32 s55, 0, 0x1c000
	s_add_u32 s52, s52, 0x80000
	s_addc_u32 s53, s53, 0
	s_mov_b32 m0, s66
	v_lshl_add_u64 v[232:233], s[52:53], 0, v[156:157]
	global_load_lds_dwordx4 v[232:233], off
	v_lshl_add_u64 v[232:233], s[52:53], 0, v[160:161]
	s_mov_b32 m0, s67
	s_nop 0
	global_load_lds_dwordx4 v[232:233], off
	v_add_u32_e32 v0, s54, v181
	ds_read_b128 v[132:135], v0
	ds_read_b128 v[136:139], v0 offset:1024
	ds_read_b128 v[140:143], v0 offset:2048
	ds_read_b128 v[144:147], v0 offset:3072
	v_add_u32_e32 v0, s55, v181
	ds_read_b128 v[148:151], v0
	ds_read_b128 v[152:155], v0 offset:1024
	ds_read_b128 v[168:171], v0 offset:2048
	ds_read_b128 v[172:175], v0 offset:3072
	ds_read_b128 v[176:179], v187 offset:32768
	ds_read_b128 v[188:191], v187 offset:33792
	ds_read_b128 v[192:195], v187 offset:34816
	ds_read_b128 v[196:199], v187 offset:35840
	ds_read_b128 v[200:203], v187 offset:36864
	ds_read_b128 v[204:207], v187 offset:37888
	ds_read_b128 v[208:211], v187 offset:38912
	ds_read_b128 v[220:223], v187 offset:39936
	s_waitcnt vmcnt(8)
	s_waitcnt lgkmcnt(0)
	s_barrier
	s_setprio 1
	s_waitcnt lgkmcnt(0)
	v_mfma_f32_16x16x32_bf16 v[128:131], v[132:135], v[176:179], v[128:131]
	v_mfma_f32_16x16x32_bf16 v[124:127], v[140:143], v[176:179], v[124:127]
	v_mfma_f32_16x16x32_bf16 v[120:123], v[132:135], v[192:195], v[120:123]
	v_mfma_f32_16x16x32_bf16 v[116:119], v[140:143], v[192:195], v[116:119]
	v_mfma_f32_16x16x32_bf16 v[112:115], v[132:135], v[200:203], v[112:115]
	v_mfma_f32_16x16x32_bf16 v[108:111], v[140:143], v[200:203], v[108:111]
	v_mfma_f32_16x16x32_bf16 v[104:107], v[132:135], v[208:211], v[104:107]
	v_mfma_f32_16x16x32_bf16 v[100:103], v[140:143], v[208:211], v[100:103]
	v_mfma_f32_16x16x32_bf16 v[128:131], v[136:139], v[188:191], v[128:131]
	v_mfma_f32_16x16x32_bf16 v[124:127], v[144:147], v[188:191], v[124:127]
	v_mfma_f32_16x16x32_bf16 v[120:123], v[136:139], v[196:199], v[120:123]
	v_mfma_f32_16x16x32_bf16 v[116:119], v[144:147], v[196:199], v[116:119]
	v_mfma_f32_16x16x32_bf16 v[112:115], v[136:139], v[204:207], v[112:115]
	v_mfma_f32_16x16x32_bf16 v[108:111], v[144:147], v[204:207], v[108:111]
	v_mfma_f32_16x16x32_bf16 v[104:107], v[136:139], v[220:223], v[104:107]
	v_mfma_f32_16x16x32_bf16 v[100:103], v[144:147], v[220:223], v[100:103]
	s_setprio 0
	s_setprio 1
	v_mfma_f32_16x16x32_bf16 v[96:99], v[148:151], v[176:179], v[96:99]
	v_mfma_f32_16x16x32_bf16 v[92:95], v[168:171], v[176:179], v[92:95]
	v_mfma_f32_16x16x32_bf16 v[88:91], v[148:151], v[192:195], v[88:91]
	v_mfma_f32_16x16x32_bf16 v[84:87], v[168:171], v[192:195], v[84:87]
	v_mfma_f32_16x16x32_bf16 v[80:83], v[148:151], v[200:203], v[80:83]
	v_mfma_f32_16x16x32_bf16 v[76:79], v[168:171], v[200:203], v[76:79]
	v_mfma_f32_16x16x32_bf16 v[72:75], v[148:151], v[208:211], v[72:75]
	v_mfma_f32_16x16x32_bf16 v[68:71], v[168:171], v[208:211], v[68:71]
	v_mfma_f32_16x16x32_bf16 v[96:99], v[152:155], v[188:191], v[96:99]
	v_mfma_f32_16x16x32_bf16 v[92:95], v[172:175], v[188:191], v[92:95]
	v_mfma_f32_16x16x32_bf16 v[88:91], v[152:155], v[196:199], v[88:91]
	v_mfma_f32_16x16x32_bf16 v[84:87], v[172:175], v[196:199], v[84:87]
	v_mfma_f32_16x16x32_bf16 v[80:83], v[152:155], v[204:207], v[80:83]
	v_mfma_f32_16x16x32_bf16 v[76:79], v[172:175], v[204:207], v[76:79]
	v_mfma_f32_16x16x32_bf16 v[72:75], v[152:155], v[220:223], v[72:75]
	v_mfma_f32_16x16x32_bf16 v[68:71], v[172:175], v[220:223], v[68:71]
	s_setprio 0
	s_barrier
; #define PG8_STAGE(bufoff, gbase, voff) do { _Pragma("unroll") for (int _i = 0; _i < 2; ++_i) \
;         __builtin_amdgcn_global_load_lds((const unsigned*)((const char*)(gbase) + (voff)[_i]), (PG8_LAS unsigned*)(lds + (bufoff) + ldsw + _i * 8192), 16, 0, 0); } while (0)
; #define PG8_LDA(dst, b, h) do { _Pragma("unroll") for (int m = 0; m < 4; ++m) _Pragma("unroll") for (int k = 0; k < 2; ++k) dst[m][k] = *(const PG8_LAS bf16x8*)(lds + PG8_SA(b, h) + aoff + m * 2048 + k * 1024); } while (0)
; #define PG8_MMA(ai, bj, At, Bt) do { __builtin_amdgcn_s_setprio(1); _Pragma("unroll") for (int m = 0; m < 4; ++m) _Pragma("unroll") for (int n = 0; n < 2; ++n) _Pragma("unroll") for (int k = 0; k < 2; ++k) \
;         acc[ai][bj][m][n] = __builtin_amdgcn_mfma_f32_16x16x32_bf16(Bt[n][k], At[m][k], acc[ai][bj][m][n], 0, 0, 0); __builtin_amdgcn_s_setprio(0); } while (0)
; #define PG8_WAIT_V(n) asm volatile("s_waitcnt vmcnt(" #n ")" ::: "memory")
; #define PG8_WAIT_L(n) asm volatile("s_waitcnt lgkmcnt(" #n ")" ::: "memory")
; #define PG8_BAR __builtin_amdgcn_s_barrier()
; #define PG8_SCHED __builtin_amdgcn_sched_barrier(0)
; template <class Epi, class Sched, bool ALIGN_EPI = false, bool SP2 = false>
; __device__ __forceinline__ void gemm_phase(PG8_LAS unsigned char* lds, const Gemm g, const Sched& S, const Epi& E) {
;     ...
;             PG8_LDA(At, 1, 1); PG8_STAGE(PG8_SB(1, 0), b3, voffB); PG8_STAGE(PG8_SB(1, 1), b3 + hstep, voffB); PG8_STAGE(PG8_SA(1, 0), a3, voffA);
;             PG8_WAIT_V(8); PG8_WAIT_L(0); PG8_BAR; PG8_MMA(1, 0, At, B0); PG8_MMA(1, 1, At, B1); PG8_BAR; PG8_SCHED;
	s_add_i32 s52, s54, s15
	v_lshl_add_u64 v[224:225], v[224:225], 0, s[88:89]
	s_mov_b32 m0, s52
	global_load_lds_dwordx4 v[224:225], off
	s_add_i32 m0, s52, 0x2000
	s_add_u32 s12, s12, 0x80080
	v_lshl_add_u64 v[224:225], v[226:227], 0, s[88:89]
	s_addc_u32 s13, s13, 0
	s_add_i32 s52, s55, s15
	global_load_lds_dwordx4 v[224:225], off
	v_lshl_add_u64 v[224:225], s[12:13], 0, v[158:159]
	s_mov_b32 m0, s52
	s_nop 0
	global_load_lds_dwordx4 v[224:225], off
	v_lshl_add_u64 v[224:225], s[12:13], 0, v[162:163]
	s_add_i32 m0, s52, 0x2000
	s_nop 0
	global_load_lds_dwordx4 v[224:225], off
	v_lshl_add_u64 v[224:225], v[228:229], 0, s[88:89]
	s_mov_b32 m0, s69
	s_nop 0
	global_load_lds_dwordx4 v[224:225], off
	v_lshl_add_u64 v[224:225], v[230:231], 0, s[88:89]
	s_mov_b32 m0, s70
	s_nop 0
	global_load_lds_dwordx4 v[224:225], off
	ds_read_b128 v[176:179], v187 offset:49152
	ds_read_b128 v[188:191], v187 offset:50176
	ds_read_b128 v[192:195], v187 offset:51200
	ds_read_b128 v[196:199], v187 offset:52224
	ds_read_b128 v[200:203], v187 offset:53248
	ds_read_b128 v[204:207], v187 offset:54272
	ds_read_b128 v[208:211], v187 offset:55296
	ds_read_b128 v[220:223], v187 offset:56320
	s_waitcnt vmcnt(8)
	s_waitcnt lgkmcnt(0)
	s_barrier
	s_setprio 1
	s_waitcnt lgkmcnt(0)
	v_mfma_f32_16x16x32_bf16 v[62:65], v[132:135], v[176:179], v[62:65]
	v_mfma_f32_16x16x32_bf16 v[58:61], v[140:143], v[176:179], v[58:61]
	v_mfma_f32_16x16x32_bf16 v[54:57], v[132:135], v[192:195], v[54:57]
	v_mfma_f32_16x16x32_bf16 v[50:53], v[140:143], v[192:195], v[50:53]
	v_mfma_f32_16x16x32_bf16 v[46:49], v[132:135], v[200:203], v[46:49]
	v_mfma_f32_16x16x32_bf16 v[42:45], v[140:143], v[200:203], v[42:45]
	v_mfma_f32_16x16x32_bf16 v[38:41], v[132:135], v[208:211], v[38:41]
	v_mfma_f32_16x16x32_bf16 v[34:37], v[140:143], v[208:211], v[34:37]
	v_mfma_f32_16x16x32_bf16 v[62:65], v[136:139], v[188:191], v[62:65]
	v_mfma_f32_16x16x32_bf16 v[58:61], v[144:147], v[188:191], v[58:61]
	v_mfma_f32_16x16x32_bf16 v[54:57], v[136:139], v[196:199], v[54:57]
	v_mfma_f32_16x16x32_bf16 v[50:53], v[144:147], v[196:199], v[50:53]
	v_mfma_f32_16x16x32_bf16 v[46:49], v[136:139], v[204:207], v[46:49]
	v_mfma_f32_16x16x32_bf16 v[42:45], v[144:147], v[204:207], v[42:45]
	v_mfma_f32_16x16x32_bf16 v[38:41], v[136:139], v[220:223], v[38:41]
	v_mfma_f32_16x16x32_bf16 v[34:37], v[144:147], v[220:223], v[34:37]
	s_setprio 0
	s_setprio 1
	v_mfma_f32_16x16x32_bf16 v[30:33], v[148:151], v[176:179], v[30:33]
	v_mfma_f32_16x16x32_bf16 v[26:29], v[168:171], v[176:179], v[26:29]
	v_mfma_f32_16x16x32_bf16 v[22:25], v[148:151], v[192:195], v[22:25]
	v_mfma_f32_16x16x32_bf16 v[18:21], v[168:171], v[192:195], v[18:21]
	v_mfma_f32_16x16x32_bf16 v[14:17], v[148:151], v[200:203], v[14:17]
	v_mfma_f32_16x16x32_bf16 v[10:13], v[168:171], v[200:203], v[10:13]
	v_mfma_f32_16x16x32_bf16 v[6:9], v[148:151], v[208:211], v[6:9]
	v_mfma_f32_16x16x32_bf16 v[2:5], v[168:171], v[208:211], v[2:5]
	v_mfma_f32_16x16x32_bf16 v[30:33], v[152:155], v[188:191], v[30:33]
	v_mfma_f32_16x16x32_bf16 v[26:29], v[172:175], v[188:191], v[26:29]
	v_mfma_f32_16x16x32_bf16 v[22:25], v[152:155], v[196:199], v[22:25]
	v_mfma_f32_16x16x32_bf16 v[18:21], v[172:175], v[196:199], v[18:21]
	v_mfma_f32_16x16x32_bf16 v[14:17], v[152:155], v[204:207], v[14:17]
	v_mfma_f32_16x16x32_bf16 v[10:13], v[172:175], v[204:207], v[10:13]
	v_mfma_f32_16x16x32_bf16 v[6:9], v[152:155], v[220:223], v[6:9]
	v_mfma_f32_16x16x32_bf16 v[2:5], v[172:175], v[220:223], v[2:5]
	s_setprio 0
	s_barrier
	s_add_i32 s12, s43, 2
	s_cmp_gt_u32 s43, 29
	s_cbranch_scc1 .LBB0_400
	s_mov_b32 s43, s12
	s_branch .LBB0_384
